# HGRN loops: NaN-canonicalizing v_max before the clamp removed (identity for finite data), three more s_nop pads replaced by real work
# speedup vs baseline: 1.0022x; 1.0012x over previous
; #define LAS __attribute__((address_space(3)))
; __device__ __forceinline__ unsigned cvt_pk_bf16(float lo, float hi) { unsigned r; asm volatile("v_cvt_pk_bf16_f32 %0, %1, %2" : "=v"(r) : "v"(lo), "v"(hi)); return r; }
; __device__ __forceinline__ float bf2f(unsigned short b) { return __uint_as_float(((unsigned)b) << 16); }
; template <bool FULL>
; __device__ __forceinline__ void hgrn_item(LAS unsigned char* lds, const bf16_t* P, bf16_t* AB, int L, int hd, const float* lbv, const float* anorm, const float* S0, const float* Dd, int ns, float* Sout, float* Dout) {
;     ...
;         float cs[4], kk[4], qv[4];
;         {
;             float run = 0.f;
; #pragma unroll
;             for (int i = 0; i < 4; ++i) { float z = bf2f(zc[i]); z = fminf(fmaxf(z, -30.f), 30.f); const float e = __expf(-z), sg = __builtin_amdgcn_rcpf(1.f + e), sn = e * sg;
;                 const float f = lb + oml * sg; run += __builtin_amdgcn_logf(f) * 0.69314718056f; cs[i] = run; kk[i] = oml * sn; qv[i] = bf2f(qc[i]); }
;             qsum[tq * 128 + k] = run;
;         }
;         __syncthreads();
;         {
;             float pre = 0.f, tot = 0.f;
; #pragma unroll
;             for (int j = 0; j < 4; ++j) { const float v = qsum[j * 128 + k]; tot += v; pre += (j < tq) ? v : 0.f; }
;             btot += tot;
;             float kh[4];
; #pragma unroll
;             for (int i = 0; i < 4; ++i) { const float b = pre + cs[i]; const float qt = qv[i] * __expf(b), kt = kk[i] * __expf(fminf(-b, 80.f)); kh[i] = kk[i] * __expf(tot - b);
;                 Qt[(4 * tq + i) * 136 + k] = (bf16_t)(cvt_pk_bf16(qt, 0.f) & 0xffffu); Kt[(4 * tq + i) * 136 + k] = (bf16_t)(cvt_pk_bf16(kt, 0.f) & 0xffffu); }
;             u32x2 kp; kp.x = cvt_pk_bf16(kh[0], kh[1]); kp.y = cvt_pk_bf16(kh[2], kh[3]);
;             *(LAS u32x2*)(KhT + k * 20 + 4 * tq) = kp;
;             if (tq == 0) dvec[k] = __expf(tot);
.LBB0_227:
	s_or_b64 exec, exec, s[4:5]
	v_lshlrev_b32_e32 v68, 16, v68
	v_med3_f32 v68, v68, s29, v225
	v_lshlrev_b32_e32 v72, 16, v72
	v_mul_f32_e32 v68, 0xbfb8aa3b, v68
	v_lshlrev_b32_e32 v70, 16, v70
	v_exp_f32_e32 v68, v68
	v_med3_f32 v72, v72, s29, v225
	v_mul_f32_e32 v72, 0xbfb8aa3b, v72
	v_med3_f32 v70, v70, s29, v225
	v_lshlrev_b32_e32 v47, 16, v47
	v_exp_f32_e32 v72, v72
	v_mul_f32_e32 v70, 0xbfb8aa3b, v70
	v_exp_f32_e32 v70, v70
	v_add_f32_e32 v69, 1.0, v68
	v_med3_f32 v47, v47, s29, v225
	v_rcp_f32_e32 v69, v69
	v_mul_f32_e32 v47, 0xbfb8aa3b, v47
	v_exp_f32_e32 v47, v47
	v_add_f32_e32 v73, 1.0, v72
	v_rcp_f32_e32 v73, v73
	v_add_f32_e32 v71, 1.0, v70
	v_rcp_f32_e32 v71, v71
	v_mul_f32_e32 v68, v68, v69
	v_mul_f32_e32 v78, v55, v68
	v_add_f32_e32 v68, 1.0, v47
	v_rcp_f32_e32 v68, v68
	v_mul_f32_e32 v72, v72, v73
	v_fma_f32 v73, v55, v73, v53
	v_log_f32_e32 v73, v73
	v_mul_f32_e32 v70, v70, v71
	v_fma_f32 v71, v55, v71, v53
	v_log_f32_e32 v71, v71
	v_fma_f32 v69, v55, v69, v53
	v_log_f32_e32 v69, v69
	v_mul_f32_e32 v47, v47, v68
	v_fma_f32 v68, v55, v68, v53
	v_log_f32_e32 v68, v68
	v_add_f32_e32 v75, v71, v73
	v_mul_f32_e32 v79, v55, v47
	v_add_f32_e32 v47, v69, v75
	v_add_f32_e32 v81, v68, v47
	ds_write_b32 v54, v81 offset:19456
	s_waitcnt lgkmcnt(0)
	s_barrier
	ds_read2st64_b32 v[68:69], v49 offset0:76 offset1:78
	ds_read2st64_b32 v[128:129], v49 offset0:80 offset1:82
	v_mul_f32_e32 v76, v55, v70
	v_mul_f32_e32 v72, v55, v72
	s_waitcnt lgkmcnt(1)
	v_add_f32_e32 v46, 0, v68
	v_cndmask_b32_e64 v68, 0, v46, s[46:47]
	v_add_f32_e32 v46, v46, v69
	v_cndmask_b32_e64 v69, 0, v69, s[44:45]
	v_add_f32_e32 v70, v68, v69
	s_waitcnt lgkmcnt(0)
	v_add_f32_e32 v46, v46, v128
	v_cndmask_b32_e64 v68, 0, v128, s[42:43]
	v_add_f32_e32 v68, v70, v68
	v_cndmask_b32_e64 v70, 0, v129, s[40:41]
	v_add_f32_e32 v71, v68, v70
	v_add_f32_e32 v68, v73, v71
	v_mov_b32_e32 v70, v129
	v_pk_add_f32 v[46:47], v[46:47], v[70:71]
	v_sub_f32_e32 v68, v46, v68
	v_exp_f32_e32 v68, v68
	v_add_f32_e32 v69, v75, v71
	v_mul_f32_e32 v68, v72, v68
	v_sub_f32_e32 v69, v46, v69
	v_exp_f32_e32 v69, v69
	v_sub_f32_e32 v47, v46, v47
	v_add_f32_e32 v67, v81, v71
	v_sub_f32_e32 v67, v46, v67
	v_exp_f32_e32 v47, v47
	v_exp_f32_e32 v67, v67
	v_mul_f32_e32 v69, v76, v69
	v_mul_f32_e32 v47, v78, v47
	v_mul_f32_e32 v67, v79, v67
	v_cvt_pk_bf16_f32 v68, v68, v69
	v_cvt_pk_bf16_f32 v69, v47, v67
	ds_write_b64 v52, v[68:69] offset:8704
	s_and_saveexec_b64 s[4:5], s[38:39]
	s_cbranch_execz .LBB0_229
	v_exp_f32_e32 v47, v46
	ds_write_b32 v49, v47 offset:18944

; #define LAS __attribute__((address_space(3)))
; __device__ __forceinline__ unsigned cvt_pk_bf16(float lo, float hi) { unsigned r; asm volatile("v_cvt_pk_bf16_f32 %0, %1, %2" : "=v"(r) : "v"(lo), "v"(hi)); return r; }
; __device__ __forceinline__ float bf2f(unsigned short b) { return __uint_as_float(((unsigned)b) << 16); }
; template <bool FULL>
; __device__ __forceinline__ void hgrn_item(LAS unsigned char* lds, const bf16_t* P, bf16_t* AB, int L, int hd, const float* lbv, const float* anorm, const float* S0, const float* Dd, int ns, float* Sout, float* Dout) {
;     ...
;         float cs[4], kk[4], qv[4];
;         {
;             float run = 0.f;
; #pragma unroll
;             for (int i = 0; i < 4; ++i) { float z = bf2f(zc[i]); z = fminf(fmaxf(z, -30.f), 30.f); const float e = __expf(-z), sg = __builtin_amdgcn_rcpf(1.f + e), sn = e * sg;
;                 const float f = lb + oml * sg; run += __builtin_amdgcn_logf(f) * 0.69314718056f; cs[i] = run; kk[i] = oml * sn; qv[i] = bf2f(qc[i]); }
;             qsum[tq * 128 + k] = run;
;         }
;         __syncthreads();
;         {
;             float pre = 0.f, tot = 0.f;
; #pragma unroll
;             for (int j = 0; j < 4; ++j) { const float v = qsum[j * 128 + k]; tot += v; pre += (j < tq) ? v : 0.f; }
;             btot += tot;
;             float kh[4];
; #pragma unroll
;             for (int i = 0; i < 4; ++i) { const float b = pre + cs[i]; const float qt = qv[i] * __expf(b), kt = kk[i] * __expf(fminf(-b, 80.f)); kh[i] = kk[i] * __expf(tot - b);
;                 Qt[(4 * tq + i) * 136 + k] = (bf16_t)(cvt_pk_bf16(qt, 0.f) & 0xffffu); Kt[(4 * tq + i) * 136 + k] = (bf16_t)(cvt_pk_bf16(kt, 0.f) & 0xffffu); }
;             u32x2 kp; kp.x = cvt_pk_bf16(kh[0], kh[1]); kp.y = cvt_pk_bf16(kh[2], kh[3]);
;             *(LAS u32x2*)(KhT + k * 20 + 4 * tq) = kp;
;             if (tq == 0) dvec[k] = __expf(tot);
.LBB0_333:
	s_or_b64 exec, exec, s[0:1]
	v_lshlrev_b32_e32 v51, 16, v41
	v_lshlrev_b32_e32 v41, 16, v44
	v_med3_f32 v41, v41, s29, v225
	v_mul_f32_e32 v41, 0xbfb8aa3b, v41
	v_exp_f32_e32 v41, v41
	v_lshlrev_b32_e32 v47, 16, v47
	v_lshlrev_b32_e32 v45, 16, v45
	v_add_f32_e32 v44, 1.0, v41
	v_rcp_f32_e32 v44, v44
	v_med3_f32 v47, v47, s29, v225
	v_mul_f32_e32 v47, 0xbfb8aa3b, v47
	v_mul_f32_e32 v41, v41, v44
	v_med3_f32 v45, v45, s29, v225
	v_mul_f32_e32 v52, v89, v41
	v_lshlrev_b32_e32 v41, 16, v42
	v_exp_f32_e32 v47, v47
	v_mul_f32_e32 v45, 0xbfb8aa3b, v45
	v_exp_f32_e32 v45, v45
	v_med3_f32 v41, v41, s29, v225
	v_mul_f32_e32 v41, 0xbfb8aa3b, v41
	v_exp_f32_e32 v41, v41
	v_add_f32_e32 v48, 1.0, v47
	v_rcp_f32_e32 v48, v48
	v_add_f32_e32 v49, 1.0, v45
	v_rcp_f32_e32 v49, v49
	v_add_f32_e32 v42, 1.0, v41
	v_rcp_f32_e32 v42, v42
	v_mul_f32_e32 v47, v47, v48
	v_fma_f32 v48, v89, v48, v103
	v_log_f32_e32 v48, v48
	v_mul_f32_e32 v45, v45, v49
	v_fma_f32 v49, v89, v49, v103
	v_log_f32_e32 v49, v49
	v_fma_f32 v44, v89, v44, v103
	v_log_f32_e32 v44, v44
	v_mul_f32_e32 v41, v41, v42
	v_fma_f32 v42, v89, v42, v103
	v_log_f32_e32 v42, v42
	v_add_f32_e32 v49, v49, v48
	v_mul_f32_e32 v54, v89, v41
	v_add_f32_e32 v41, v44, v49
	v_add_f32_e32 v56, v42, v41
	v_lshlrev_b32_e32 v53, 16, v43
	ds_write_b32 v92, v56 offset:19456
	s_waitcnt lgkmcnt(0)
	s_barrier
	ds_read2st64_b32 v[42:43], v93 offset0:76 offset1:78
	ds_read2st64_b32 v[128:129], v93 offset0:80 offset1:82
	v_lshlrev_b32_e32 v55, 16, v40
	v_mul_f32_e32 v50, v89, v45
	v_lshlrev_b32_e32 v46, 16, v46
	v_mul_f32_e32 v47, v89, v47
	s_waitcnt lgkmcnt(1)
	v_add_f32_e32 v40, 0, v42
	v_cndmask_b32_e64 v42, 0, v40, s[40:41]
	v_add_f32_e32 v40, v40, v43
	v_cndmask_b32_e64 v43, 0, v43, s[42:43]
	v_add_f32_e32 v44, v42, v43
	s_waitcnt lgkmcnt(0)
	v_add_f32_e32 v40, v40, v128
	v_cndmask_b32_e64 v42, 0, v128, s[44:45]
	v_add_f32_e32 v42, v44, v42
	v_cndmask_b32_e64 v44, 0, v129, s[46:47]
	v_add_f32_e32 v45, v42, v44
	v_add_f32_e32 v42, v48, v45
	v_exp_f32_e32 v44, v42
	s_nop 0
	v_mul_f32_e32 v46, v44, v46
	v_min_f32_e64 v44, -v42, s99
	v_exp_f32_e32 v44, v44
	s_nop 0
	v_mul_f32_e32 v48, v47, v44
	v_mov_b32_e32 v44, v129
	v_cvt_pk_bf16_f32 v43, v46, v48
	ds_write_b16 v96, v43
	ds_write_b16_d16_hi v96, v43 offset:4352
	v_add_f32_e32 v43, v49, v45
	v_pk_add_f32 v[40:41], v[40:41], v[44:45]
	v_exp_f32_e32 v44, v43
	v_min_f32_e64 v46, -v43, s99
	v_exp_f32_e32 v46, v46
	v_mul_f32_e32 v44, v44, v51
	v_mul_f32_e32 v46, v50, v46
	v_cvt_pk_bf16_f32 v44, v44, v46
	ds_write_b16 v96, v44 offset:272
	ds_write_b16_d16_hi v96, v44 offset:4624
	v_exp_f32_e32 v44, v41
	v_min_f32_e64 v46, -v41, s99
	v_exp_f32_e32 v46, v46
	v_mul_f32_e32 v44, v44, v53
	v_mul_f32_e32 v46, v52, v46
	v_cvt_pk_bf16_f32 v44, v44, v46
	ds_write_b16 v96, v44 offset:544
	ds_write_b16_d16_hi v96, v44 offset:4896
	v_add_f32_e32 v44, v56, v45
	v_sub_f32_e32 v42, v40, v42
	v_sub_f32_e32 v43, v40, v43
	v_sub_f32_e32 v41, v40, v41
	v_exp_f32_e32 v45, v44
	v_min_f32_e64 v46, -v44, s99
	v_sub_f32_e32 v44, v40, v44
	v_exp_f32_e32 v42, v42
	v_exp_f32_e32 v43, v43
	v_exp_f32_e32 v41, v41
	v_exp_f32_e32 v46, v46
	v_exp_f32_e32 v44, v44
	v_mul_f32_e32 v45, v45, v55
	v_mul_f32_e32 v42, v47, v42
	v_mul_f32_e32 v43, v50, v43
	v_mul_f32_e32 v41, v52, v41
	v_mul_f32_e32 v46, v54, v46
	v_mul_f32_e32 v44, v54, v44
	v_cvt_pk_bf16_f32 v45, v45, v46
	ds_write_b16 v96, v45 offset:816
	ds_write_b16_d16_hi v96, v45 offset:5168
	v_cvt_pk_bf16_f32 v42, v42, v43
	v_cvt_pk_bf16_f32 v43, v41, v44
	ds_write_b64 v98, v[42:43] offset:8704
	s_and_saveexec_b64 s[0:1], s[36:37]
	s_cbranch_execz .LBB0_335
	v_exp_f32_e32 v40, v40
	ds_write_b32 v93, v40 offset:18944

; #define LAS __attribute__((address_space(3)))
; template <bool FULL>
; __device__ __forceinline__ void hgrn_item(LAS unsigned char* lds, const bf16_t* P, bf16_t* AB, int L, int hd, const float* lbv, const float* anorm, const float* S0, const float* Dd, int ns, float* Sout, float* Dout) {
;     ...
;         f32x4 acco = (f32x4){0.f, 0.f, 0.f, 0.f};
;         {
;             const u32x2 vv = *(const LAS u32x2*)(VsT + (16 * w + c16) * 20 + 4 * q4);
;             const bf16x4 vf = __builtin_bit_cast(bf16x4, vv);
;             if (FULL) {
;             bf16x8 qf[4], kf[4];
; #pragma unroll
;             for (int kq = 0; kq < 4; ++kq) {
;                 const u32x2 a0 = *(const LAS u32x2*)(Qt + c16 * 136 + 32 * kq + 4 * q4), a1 = *(const LAS u32x2*)(Qt + c16 * 136 + 32 * kq + 16 + 4 * q4);
;                 const u32x2 b0 = *(const LAS u32x2*)(Kt + c16 * 136 + 32 * kq + 4 * q4), b1 = *(const LAS u32x2*)(Kt + c16 * 136 + 32 * kq + 16 + 4 * q4);
;                 u32x4 qa = (u32x4){a0.x, a0.y, a1.x, a1.y}, ka = (u32x4){b0.x, b0.y, b1.x, b1.y};
;                 qf[kq] = __builtin_bit_cast(bf16x8, qa); kf[kq] = __builtin_bit_cast(bf16x8, ka);
;             }
;             f32x4 accA = (f32x4){0.f, 0.f, 0.f, 0.f};
; #pragma unroll
;             for (int kq = 0; kq < 4; ++kq) accA = __builtin_amdgcn_mfma_f32_16x16x32_bf16(kf[kq], qf[kq], accA, 0, 0, 0);
; #pragma unroll
;             for (int j = 0; j < 4; ++j) accA[j] = (c16 >= 4 * q4 + j) ? accA[j] : 0.f;
;             u32x2 pa; pa.x = cvt_pk_bf16(accA[0], accA[1]); pa.y = cvt_pk_bf16(accA[2], accA[3]);
;             const bf16x4 pA = __builtin_bit_cast(bf16x4, pa);
;             acco = __builtin_amdgcn_mfma_f32_16x16x16bf16_1k(pA, vf, (f32x4){0.f, 0.f, 0.f, 0.f}, 0, 0, 0);
; #pragma unroll
;             for (int kq = 0; kq < 4; ++kq) {
;                 u32x4 sp; sp.x = cvt_pk_bf16(accS[2 * kq][0], accS[2 * kq][1]); sp.y = cvt_pk_bf16(accS[2 * kq][2], accS[2 * kq][3]);
;                 sp.z = cvt_pk_bf16(accS[2 * kq + 1][0], accS[2 * kq + 1][1]); sp.w = cvt_pk_bf16(accS[2 * kq + 1][2], accS[2 * kq + 1][3]);
;                 acco = __builtin_amdgcn_mfma_f32_16x16x32_bf16(qf[kq], __builtin_bit_cast(bf16x8, sp), acco, 0, 0, 0);
;             }
;             }
; #pragma unroll
;             for (int mt = 0; mt < 8; ++mt) {
;                 const u32x2 kh2 = *(const LAS u32x2*)(KhT + (16 * mt + c16) * 20 + 4 * q4);
.LBB0_337:
	s_or_b64 exec, exec, s[0:1]
	s_waitcnt lgkmcnt(0)
	s_barrier
	ds_read_b64 v[82:83], v99 offset:13824
	ds_read2_b64 v[36:39], v97 offset1:4
	v_add_u32_e32 v64, 0x1000, v97
	ds_read2_b64 v[52:55], v64 offset0:32 offset1:36
	ds_read2_b64 v[40:43], v97 offset0:8 offset1:12
	ds_read2_b64 v[56:59], v64 offset0:40 offset1:44
	ds_read2_b64 v[44:47], v97 offset0:16 offset1:20
	ds_read2_b64 v[60:63], v64 offset0:48 offset1:52
	ds_read2_b64 v[48:51], v97 offset0:24 offset1:28
	ds_read2_b64 v[64:67], v64 offset0:56 offset1:60
	v_add_u32_e32 v116, v91, v90
	v_add_u32_e32 v208, 0x2000, v100
	v_add_u32_e32 v209, 0x2400, v100
	ds_read_b128 v[156:159], v116 offset:18944
	ds_read_b128 v[160:163], v116 offset:19008
	ds_read2_b64 v[118:121], v208 offset0:64 offset1:144
	ds_read_b128 v[164:167], v116 offset:19072
	ds_read_b128 v[168:171], v116 offset:19136
	ds_read2_b64 v[196:199], v209 offset0:96 offset1:176
	s_waitcnt lgkmcnt(12)
	v_mfma_f32_16x16x32_bf16 v[52:55], v[52:55], v[36:39], 0
	v_add_u32_e32 v210, 0x2800, v100
	v_add_u32_e32 v211, 0x3000, v100
	s_waitcnt lgkmcnt(10)
	v_mfma_f32_16x16x32_bf16 v[52:55], v[56:59], v[40:43], v[52:55]
	s_waitcnt lgkmcnt(8)
	v_mfma_f32_16x16x32_bf16 v[52:55], v[60:63], v[44:47], v[52:55]
	s_waitcnt lgkmcnt(6)
	v_mfma_f32_16x16x32_bf16 v[52:55], v[64:67], v[48:51], v[52:55]
	ds_read_b128 v[172:175], v116 offset:19200
	ds_read_b128 v[176:179], v116 offset:19264
	ds_read2_b64 v[200:203], v210 offset0:128 offset1:208
	ds_read_b128 v[180:183], v116 offset:19328
	ds_read_b128 v[184:187], v116 offset:19392
	ds_read2_b64 v[204:207], v211 offset0:32 offset1:112
	s_nop 3
	v_cndmask_b32_e64 v52, v52, 0, s[48:49]
	v_cndmask_b32_e64 v53, 0, v53, s[50:51]
	v_cndmask_b32_e64 v54, v54, 0, s[52:53]
	v_cndmask_b32_e64 v55, v55, 0, s[54:55]
	v_cvt_pk_bf16_f32 v52, v52, v53
	v_cvt_pk_bf16_f32 v53, v54, v55
	v_cvt_pk_bf16_f32 v56, v24, v25
	v_cvt_pk_bf16_f32 v57, v26, v27
	v_cvt_pk_bf16_f32 v58, v28, v29
	v_cvt_pk_bf16_f32 v59, v30, v31
	v_cvt_pk_bf16_f32 v60, v20, v21
	v_cvt_pk_bf16_f32 v61, v22, v23
	v_cvt_pk_bf16_f32 v62, v16, v17
	v_cvt_pk_bf16_f32 v63, v18, v19
	v_cvt_pk_bf16_f32 v64, v12, v13
	v_cvt_pk_bf16_f32 v65, v14, v15
	v_cvt_pk_bf16_f32 v66, v8, v9
	v_cvt_pk_bf16_f32 v67, v10, v11
	v_cvt_pk_bf16_f32 v68, v4, v5
	v_cvt_pk_bf16_f32 v69, v6, v7
	v_cvt_pk_bf16_f32 v70, v0, v1
	v_cvt_pk_bf16_f32 v71, v2, v3
	v_mfma_f32_16x16x16_bf16 v[52:55], v[52:53], v[82:83], 0
	s_waitcnt lgkmcnt(6)
	v_pk_mul_f32 v[24:25], v[24:25], v[156:157]
	v_pk_mul_f32 v[26:27], v[26:27], v[158:159]
	v_mfma_f32_16x16x32_bf16 v[36:39], v[36:39], v[56:59], v[52:55]
	v_pk_mul_f32 v[28:29], v[28:29], v[160:161]
	v_pk_mul_f32 v[30:31], v[30:31], v[162:163]
	v_mfma_f32_16x16x16_bf16 v[24:27], v[118:119], v[82:83], v[24:27]
	v_pk_mul_f32 v[20:21], v[20:21], v[164:165]
	v_mfma_f32_16x16x16_bf16 v[28:31], v[120:121], v[82:83], v[28:31]
	v_pk_mul_f32 v[22:23], v[22:23], v[166:167]
	v_mfma_f32_16x16x32_bf16 v[36:39], v[40:43], v[60:63], v[36:39]
	v_pk_mul_f32 v[16:17], v[16:17], v[168:169]
	v_pk_mul_f32 v[18:19], v[18:19], v[170:171]
	v_mfma_f32_16x16x16_bf16 v[20:23], v[196:197], v[82:83], v[20:23]
	s_waitcnt lgkmcnt(3)
	v_mfma_f32_16x16x16_bf16 v[16:19], v[198:199], v[82:83], v[16:19]
	v_pk_mul_f32 v[12:13], v[12:13], v[172:173]
	v_pk_mul_f32 v[14:15], v[14:15], v[174:175]
	v_mfma_f32_16x16x32_bf16 v[36:39], v[44:47], v[64:67], v[36:39]
	v_pk_mul_f32 v[8:9], v[8:9], v[176:177]
	v_pk_mul_f32 v[10:11], v[10:11], v[178:179]
	v_mfma_f32_16x16x16_bf16 v[12:15], v[200:201], v[82:83], v[12:15]
	s_waitcnt lgkmcnt(0)
	v_mfma_f32_16x16x16_bf16 v[8:11], v[202:203], v[82:83], v[8:11]
	v_pk_mul_f32 v[4:5], v[4:5], v[180:181]
	v_mfma_f32_16x16x32_bf16 v[36:39], v[48:51], v[68:71], v[36:39]
	v_mul_f32_e64 v6, v6, v182
	v_mul_f32_e64 v7, v7, v183
	v_pk_mul_f32 v[0:1], v[0:1], v[184:185]
	v_pk_mul_f32 v[2:3], v[2:3], v[186:187]
	s_nop 3
	v_pk_mul_f32 v[44:45], v[38:39], v[38:39]
	v_pk_mul_f32 v[42:43], v[36:37], v[36:37]
	v_mfma_f32_16x16x16_bf16 v[4:7], v[204:205], v[82:83], v[4:7]
	v_add_f32_dpp v44, v44, v44 row_ror:8 row_mask:0xf bank_mask:0xf bound_ctrl:1
	v_add_f32_dpp v45, v45, v45 row_ror:8 row_mask:0xf bank_mask:0xf bound_ctrl:1
	v_add_f32_dpp v42, v42, v42 row_ror:8 row_mask:0xf bank_mask:0xf bound_ctrl:1
	v_add_f32_dpp v43, v43, v43 row_ror:8 row_mask:0xf bank_mask:0xf bound_ctrl:1
	v_mfma_f32_16x16x16_bf16 v[0:3], v[206:207], v[82:83], v[0:3]
	v_add_f32_dpp v44, v44, v44 row_ror:4 row_mask:0xf bank_mask:0xf bound_ctrl:1
	v_add_f32_dpp v45, v45, v45 row_ror:4 row_mask:0xf bank_mask:0xf bound_ctrl:1
	v_add_f32_dpp v42, v42, v42 row_ror:4 row_mask:0xf bank_mask:0xf bound_ctrl:1
	v_add_f32_dpp v43, v43, v43 row_ror:4 row_mask:0xf bank_mask:0xf bound_ctrl:1
	v_add_f32_dpp v44, v44, v44 row_ror:2 row_mask:0xf bank_mask:0xf bound_ctrl:1
	v_add_f32_dpp v45, v45, v45 row_ror:2 row_mask:0xf bank_mask:0xf bound_ctrl:1
	v_add_f32_dpp v42, v42, v42 row_ror:2 row_mask:0xf bank_mask:0xf bound_ctrl:1
	v_add_f32_dpp v43, v43, v43 row_ror:2 row_mask:0xf bank_mask:0xf bound_ctrl:1
	v_add_f32_dpp v44, v44, v44 row_ror:1 row_mask:0xf bank_mask:0xf bound_ctrl:1
	v_add_f32_dpp v45, v45, v45 row_ror:1 row_mask:0xf bank_mask:0xf bound_ctrl:1
	v_add_f32_dpp v42, v42, v42 row_ror:1 row_mask:0xf bank_mask:0xf bound_ctrl:1
	v_add_f32_dpp v43, v43, v43 row_ror:1 row_mask:0xf bank_mask:0xf bound_ctrl:1
	s_and_saveexec_b64 s[0:1], s[38:39]
	s_cbranch_execz .LBB0_330
	ds_write_b128 v95, v[42:45] offset:21504
	s_branch .LBB0_330
